# baseline (speedup 1.0000x reference)
; #define LAS __attribute__((address_space(3)))
; DI float shdown(float v, int lane, int d) { return __builtin_bit_cast(float, __builtin_amdgcn_ds_bpermute(((lane + d) & 63) << 2, __builtin_bit_cast(int, v))); }
; DI void mix_sb(CP& p, int l, int it, LAS unsigned char* lds) {
;     ...
;     for (int kt = 0; kt < 4; ++kt) {
;       f32x4 a = {0.f, 0.f, 0.f, 0.f};
; #pragma unroll
;       for (int ds = 0; ds < 4; ++ds) {
;         const bf16x8 kf = *(const LAS bf16x8*)(kbuf + (16 * kt + fr) * KSTR + 32 * ds + 8 * fq);
;         a = __builtin_amdgcn_mfma_f32_16x16x32_bf16(kf, qf[ds], a, 0, 0, 0);
;       }
;       sc[kt] = a;
;     }
;     float ls[4][4], lk[4][4], T[4], F[4], tot[4];
; #pragma unroll
;     for (int kt = 0; kt < 4; ++kt) {
; #pragma unroll
;       for (int j = 0; j < 4; ++j) {
;         const float z = sc[kt][j];
;         const int spos = kb * 64 + kt * 16 + 4 * fq + j;
;         const bool causal = valid && (spos < tq);
;         const float lsv = fminf(z, 0.f) - __logf(1.f + __expf(-fabsf(z)));
;         ls[kt][j] = causal ? lsv : -1e30f;
;         lk[kt][j] = causal ? (lsv - z) : 0.f;
;       }
;       T[kt] = (lk[kt][0] + lk[kt][1]) + (lk[kt][2] + lk[kt][3]);
;       const float t1 = shdown(T[kt], lane, 16), t2 = shdown(T[kt], lane, 32), t3 = shdown(T[kt], lane, 48);
;       F[kt] = (fq < 3 ? t1 : 0.f) + (fq < 2 ? t2 : 0.f) + (fq < 1 ? t3 : 0.f);
;       float tt = T[kt] + shx<16>(T[kt], lane); tt += shx<32>(tt, lane); tot[kt] = tt;
.LBB0_226:
	s_and_b32 s15, s14, 1
	s_mul_i32 s0, s15, 0x8680
	s_add_i32 s24, s0, 0x100
	v_add3_u32 v93, s24, v84, v107
	ds_read_b128 v[150:153], v93
	ds_read_b128 v[154:157], v93 offset:64
	ds_read_b128 v[158:161], v93 offset:128
	ds_read_b128 v[162:165], v93 offset:192
	ds_read_b128 v[166:169], v93 offset:4352
	ds_read_b128 v[170:173], v93 offset:4416
	ds_read_b128 v[174:177], v93 offset:4480
	ds_read_b128 v[178:181], v93 offset:4544
	ds_read_b128 v[182:185], v93 offset:8704
	ds_read_b128 v[186:189], v93 offset:8768
	ds_read_b128 v[190:193], v93 offset:8832
	ds_read_b128 v[194:197], v93 offset:8896
	s_waitcnt lgkmcnt(8)
	v_mfma_f32_16x16x32_bf16 v[76:79], v[150:153], v[32:35], 0
	v_mfma_f32_16x16x32_bf16 v[76:79], v[154:157], v[36:39], v[76:79]
	v_mfma_f32_16x16x32_bf16 v[76:79], v[158:161], v[40:43], v[76:79]
	v_mfma_f32_16x16x32_bf16 v[76:79], v[162:165], v[44:47], v[76:79]
	ds_read_b128 v[198:201], v93 offset:13056
	ds_read_b128 v[202:205], v93 offset:13120
	ds_read_b128 v[206:209], v93 offset:13184
	ds_read_b128 v[210:213], v93 offset:13248
	v_or_b32_e32 v93, s5, v102
	v_cmp_lt_i32_e32 vcc, v93, v98
	s_waitcnt lgkmcnt(8)
	v_mfma_f32_16x16x32_bf16 v[72:75], v[166:169], v[32:35], 0
	v_mfma_f32_16x16x32_bf16 v[72:75], v[170:173], v[36:39], v[72:75]
	v_mfma_f32_16x16x32_bf16 v[72:75], v[174:177], v[40:43], v[72:75]
	v_mfma_f32_16x16x32_bf16 v[72:75], v[178:181], v[44:47], v[72:75]
	s_waitcnt lgkmcnt(4)
	v_mfma_f32_16x16x32_bf16 v[68:71], v[182:185], v[32:35], 0
	v_mfma_f32_16x16x32_bf16 v[68:71], v[186:189], v[36:39], v[68:71]
	v_mfma_f32_16x16x32_bf16 v[68:71], v[190:193], v[40:43], v[68:71]
	v_mfma_f32_16x16x32_bf16 v[68:71], v[194:197], v[44:47], v[68:71]
	s_waitcnt lgkmcnt(0)
	v_mfma_f32_16x16x32_bf16 v[64:67], v[198:201], v[32:35], 0
	v_mfma_f32_16x16x32_bf16 v[64:67], v[202:205], v[36:39], v[64:67]
	v_mfma_f32_16x16x32_bf16 v[64:67], v[206:209], v[40:43], v[64:67]
	v_mfma_f32_16x16x32_bf16 v[64:67], v[210:213], v[44:47], v[64:67]
	v_mul_f32_e64 v95, |v76|, s93
	v_exp_f32_e32 v95, v95
	v_max_f32_e32 v94, v76, v76
	v_min_f32_e32 v94, 0, v94
	s_and_b64 vcc, s[68:69], vcc
	v_add_f32_e32 v95, 1.0, v95
	v_cmp_gt_f32_e64 s[16:17], s81, v95
	s_nop 1
	v_cndmask_b32_e64 v96, 0, 32, s[16:17]
	v_ldexp_f32 v95, v95, v96
	v_log_f32_e32 v95, v95
	s_nop 0
	v_mul_f32_e32 v96, 0x3f317217, v95
	v_fma_f32 v96, v95, s48, -v96
	v_fmac_f32_e32 v96, 0x3377d1cf, v95
	v_fmac_f32_e32 v96, 0x3f317217, v95
	v_cmp_lt_f32_e64 s[18:19], |v95|, s49
	s_nop 1
	v_cndmask_b32_e64 v95, v95, v96, s[18:19]
	v_cndmask_b32_e64 v96, 0, v238, s[16:17]
	v_sub_f32_e32 v95, v95, v96
	v_sub_f32_e32 v94, v94, v95
	v_mul_f32_e64 v95, |v77|, s93
	v_exp_f32_e32 v95, v95
	v_cndmask_b32_e32 v112, v239, v94, vcc
	v_sub_f32_e32 v76, v94, v76
	v_or_b32_e32 v94, 1, v93
	v_add_f32_e32 v95, 1.0, v95
	v_cmp_gt_f32_e64 s[16:17], s81, v95
	v_cndmask_b32_e32 v76, 0, v76, vcc
	v_cmp_lt_i32_e32 vcc, v94, v98
	v_cndmask_b32_e64 v96, 0, 32, s[16:17]
	v_ldexp_f32 v95, v95, v96
	v_log_f32_e32 v95, v95
	v_max_f32_e32 v94, v77, v77
	v_min_f32_e32 v94, 0, v94
	s_and_b64 vcc, s[68:69], vcc
	v_mul_f32_e32 v96, 0x3f317217, v95
	v_fma_f32 v96, v95, s48, -v96
	v_fmac_f32_e32 v96, 0x3377d1cf, v95
	v_fmac_f32_e32 v96, 0x3f317217, v95
	v_cmp_lt_f32_e64 s[18:19], |v95|, s49
	s_nop 1
	v_cndmask_b32_e64 v95, v95, v96, s[18:19]
	v_cndmask_b32_e64 v96, 0, v238, s[16:17]
	v_sub_f32_e32 v95, v95, v96
	v_sub_f32_e32 v94, v94, v95
	v_cndmask_b32_e32 v113, v239, v94, vcc
	v_sub_f32_e32 v77, v94, v77
	v_mul_f32_e64 v94, |v78|, s93
	v_exp_f32_e32 v94, v94
	v_cndmask_b32_e32 v114, 0, v77, vcc
	v_or_b32_e32 v77, 2, v93
	v_cmp_lt_i32_e32 vcc, v77, v98
	v_add_f32_e32 v94, 1.0, v94
	v_cmp_gt_f32_e64 s[16:17], s81, v94
	v_max_f32_e32 v77, v78, v78
	v_min_f32_e32 v77, 0, v77
	v_cndmask_b32_e64 v95, 0, 32, s[16:17]
	v_ldexp_f32 v94, v94, v95
	v_log_f32_e32 v94, v94
	s_and_b64 vcc, s[68:69], vcc
	v_add_f32_e32 v76, v76, v114
	v_mul_f32_e32 v95, 0x3f317217, v94
	v_fma_f32 v95, v94, s48, -v95
	v_fmac_f32_e32 v95, 0x3377d1cf, v94
	v_fmac_f32_e32 v95, 0x3f317217, v94
	v_cmp_lt_f32_e64 s[18:19], |v94|, s49
	s_nop 1
	v_cndmask_b32_e64 v94, v94, v95, s[18:19]
	v_cndmask_b32_e64 v95, 0, v238, s[16:17]
	v_sub_f32_e32 v94, v94, v95
	v_sub_f32_e32 v77, v77, v94
	v_mul_f32_e64 v94, |v79|, s93
	v_exp_f32_e32 v94, v94
	v_cndmask_b32_e32 v115, v239, v77, vcc
	v_sub_f32_e32 v77, v77, v78
	v_or_b32_e32 v78, 3, v93
	v_add_f32_e32 v94, 1.0, v94
	v_cmp_gt_f32_e64 s[16:17], s81, v94
	v_cndmask_b32_e32 v77, 0, v77, vcc
	v_cmp_lt_i32_e32 vcc, v78, v98
	v_cndmask_b32_e64 v95, 0, 32, s[16:17]
	v_ldexp_f32 v94, v94, v95
	v_log_f32_e32 v94, v94
	v_max_f32_e32 v78, v79, v79
	v_min_f32_e32 v78, 0, v78
	s_and_b64 vcc, s[68:69], vcc
	v_mul_f32_e32 v95, 0x3f317217, v94
	v_fma_f32 v95, v94, s48, -v95
	v_fmac_f32_e32 v95, 0x3377d1cf, v94
	v_fmac_f32_e32 v95, 0x3f317217, v94
	v_cmp_lt_f32_e64 s[18:19], |v94|, s49
	s_nop 1
	v_cndmask_b32_e64 v94, v94, v95, s[18:19]
	v_cndmask_b32_e64 v95, 0, v238, s[16:17]
	v_sub_f32_e32 v94, v94, v95
	v_sub_f32_e32 v78, v78, v94
	v_cndmask_b32_e32 v116, v239, v78, vcc
	v_sub_f32_e32 v78, v78, v79
	v_cndmask_b32_e32 v117, 0, v78, vcc
	v_add_f32_e32 v118, v77, v117
	v_add_f32_e32 v77, v76, v118
	ds_bpermute_b32 v79, v104, v77
	ds_bpermute_b32 v76, v103, v77
	ds_bpermute_b32 v95, v105, v77
	s_waitcnt lgkmcnt(2)
	v_cndmask_b32_e64 v94, 0, v79, s[10:11]
	ds_swizzle_b32 v79, v77 offset:swizzle(SWAP,16)
	s_waitcnt lgkmcnt(2)
	v_cndmask_b32_e64 v78, v76, 0, s[8:9]
	s_waitcnt lgkmcnt(1)
	v_cndmask_b32_e64 v76, 0, v95, s[12:13]
	s_waitcnt lgkmcnt(0)
; DI float shdown(float v, int lane, int d) { return __builtin_bit_cast(float, __builtin_amdgcn_ds_bpermute(((lane + d) & 63) << 2, __builtin_bit_cast(int, v))); }
; DI void mix_sb(CP& p, int l, int it, LAS unsigned char* lds) {
;     ...
;     for (int kt = 0; kt < 4; ++kt) {
; #pragma unroll
;       for (int j = 0; j < 4; ++j) {
;         const float z = sc[kt][j];
;         const int spos = kb * 64 + kt * 16 + 4 * fq + j;
;         const bool causal = valid && (spos < tq);
;         const float lsv = fminf(z, 0.f) - __logf(1.f + __expf(-fabsf(z)));
;         ls[kt][j] = causal ? lsv : -1e30f;
;         lk[kt][j] = causal ? (lsv - z) : 0.f;
;       }
;       T[kt] = (lk[kt][0] + lk[kt][1]) + (lk[kt][2] + lk[kt][3]);
;       const float t1 = shdown(T[kt], lane, 16), t2 = shdown(T[kt], lane, 32), t3 = shdown(T[kt], lane, 48);
;       F[kt] = (fq < 3 ? t1 : 0.f) + (fq < 2 ? t2 : 0.f) + (fq < 1 ? t3 : 0.f);
;       float tt = T[kt] + shx<16>(T[kt], lane); tt += shx<32>(tt, lane); tot[kt] = tt;
	v_add_f32_e32 v110, v77, v79
	v_mul_f32_e64 v79, |v72|, s93
	v_exp_f32_e32 v79, v79
	v_or_b32_e32 v77, 16, v93
	v_cmp_lt_i32_e32 vcc, v77, v98
	v_max_f32_e32 v77, v72, v72
	v_add_f32_e32 v79, 1.0, v79
	v_cmp_gt_f32_e64 s[16:17], s81, v79
	v_min_f32_e32 v77, 0, v77
	s_and_b64 vcc, s[68:69], vcc
	v_cndmask_b32_e64 v95, 0, 32, s[16:17]
	v_ldexp_f32 v79, v79, v95
	v_log_f32_e32 v79, v79
	ds_bpermute_b32 v111, v104, v110
	v_mul_f32_e32 v95, 0x3f317217, v79
	v_fma_f32 v95, v79, s48, -v95
	v_fmac_f32_e32 v95, 0x3377d1cf, v79
	v_fmac_f32_e32 v95, 0x3f317217, v79
	v_cmp_lt_f32_e64 s[18:19], |v79|, s49
	s_nop 1
	v_cndmask_b32_e64 v79, v79, v95, s[18:19]
	v_cndmask_b32_e64 v95, 0, v238, s[16:17]
	v_sub_f32_e32 v79, v79, v95
	v_mul_f32_e64 v95, |v73|, s93
	v_exp_f32_e32 v95, v95
	v_sub_f32_e32 v79, v77, v79
	v_cndmask_b32_e32 v77, v239, v79, vcc
	v_sub_f32_e32 v72, v79, v72
	v_add_f32_e32 v95, 1.0, v95
	v_cmp_gt_f32_e64 s[16:17], s81, v95
	v_or_b32_e32 v79, 17, v93
	v_cndmask_b32_e32 v72, 0, v72, vcc
	v_cndmask_b32_e64 v96, 0, 32, s[16:17]
	v_ldexp_f32 v95, v95, v96
	v_log_f32_e32 v95, v95
	v_cmp_lt_i32_e32 vcc, v79, v98
	v_max_f32_e32 v79, v73, v73
	v_min_f32_e32 v79, 0, v79
	v_mul_f32_e32 v96, 0x3f317217, v95
	v_fma_f32 v96, v95, s48, -v96
	v_fmac_f32_e32 v96, 0x3377d1cf, v95
	v_fmac_f32_e32 v96, 0x3f317217, v95
	v_cmp_lt_f32_e64 s[18:19], |v95|, s49
	s_and_b64 vcc, s[68:69], vcc
	s_nop 0
	v_cndmask_b32_e64 v95, v95, v96, s[18:19]
	v_cndmask_b32_e64 v96, 0, v238, s[16:17]
	v_sub_f32_e32 v95, v95, v96
	v_sub_f32_e32 v79, v79, v95
	v_cndmask_b32_e32 v95, v239, v79, vcc
	v_sub_f32_e32 v73, v79, v73
	v_mul_f32_e64 v79, |v74|, s93
	v_exp_f32_e32 v79, v79
	v_cndmask_b32_e32 v119, 0, v73, vcc
	v_or_b32_e32 v73, 18, v93
	v_cmp_lt_i32_e32 vcc, v73, v98
	v_add_f32_e32 v79, 1.0, v79
	v_cmp_gt_f32_e64 s[16:17], s81, v79
	v_max_f32_e32 v73, v74, v74
	v_min_f32_e32 v73, 0, v73
	v_cndmask_b32_e64 v96, 0, 32, s[16:17]
	v_ldexp_f32 v79, v79, v96
	v_log_f32_e32 v79, v79
	s_and_b64 vcc, s[68:69], vcc
	v_add_f32_e32 v72, v72, v119
	v_mul_f32_e32 v96, 0x3f317217, v79
	v_fma_f32 v96, v79, s48, -v96
	v_fmac_f32_e32 v96, 0x3377d1cf, v79
	v_fmac_f32_e32 v96, 0x3f317217, v79
	v_cmp_lt_f32_e64 s[18:19], |v79|, s49
	s_nop 1
	v_cndmask_b32_e64 v79, v79, v96, s[18:19]
	v_cndmask_b32_e64 v96, 0, v238, s[16:17]
	v_sub_f32_e32 v79, v79, v96
	v_sub_f32_e32 v73, v73, v79
	v_mul_f32_e64 v79, |v75|, s93
	v_exp_f32_e32 v79, v79
	v_cndmask_b32_e32 v120, v239, v73, vcc
	v_sub_f32_e32 v73, v73, v74
	v_or_b32_e32 v74, 19, v93
	v_add_f32_e32 v79, 1.0, v79
	v_cmp_gt_f32_e64 s[16:17], s81, v79
	v_cndmask_b32_e32 v73, 0, v73, vcc
	v_cmp_lt_i32_e32 vcc, v74, v98
	v_cndmask_b32_e64 v96, 0, 32, s[16:17]
	v_ldexp_f32 v79, v79, v96
	v_log_f32_e32 v79, v79
	v_max_f32_e32 v74, v75, v75
	v_min_f32_e32 v74, 0, v74
	s_and_b64 vcc, s[68:69], vcc
	v_mul_f32_e32 v96, 0x3f317217, v79
	v_fma_f32 v96, v79, s48, -v96
	v_fmac_f32_e32 v96, 0x3377d1cf, v79
	v_fmac_f32_e32 v96, 0x3f317217, v79
	v_cmp_lt_f32_e64 s[18:19], |v79|, s49
	s_nop 1
	v_cndmask_b32_e64 v79, v79, v96, s[18:19]
	v_cndmask_b32_e64 v96, 0, v238, s[16:17]
	v_sub_f32_e32 v79, v79, v96
	v_sub_f32_e32 v74, v74, v79
	v_cndmask_b32_e32 v121, v239, v74, vcc
	v_sub_f32_e32 v74, v74, v75
	v_cndmask_b32_e32 v122, 0, v74, vcc
	v_add_f32_e32 v123, v73, v122
	v_add_f32_e32 v73, v72, v123
	ds_bpermute_b32 v75, v104, v73
	ds_bpermute_b32 v72, v103, v73
	ds_bpermute_b32 v79, v105, v73
	s_waitcnt lgkmcnt(2)
	v_cndmask_b32_e64 v96, 0, v75, s[10:11]
	ds_swizzle_b32 v75, v73 offset:swizzle(SWAP,16)
	s_waitcnt lgkmcnt(2)
	v_cndmask_b32_e64 v74, v72, 0, s[8:9]
	s_waitcnt lgkmcnt(1)
	v_cndmask_b32_e64 v72, 0, v79, s[12:13]
	s_waitcnt lgkmcnt(0)
	v_add_f32_e32 v73, v73, v75
	ds_bpermute_b32 v75, v104, v73
	s_waitcnt lgkmcnt(0)
	v_add_f32_e32 v79, v73, v75
	v_mul_f32_e64 v75, |v68|, s93
	v_exp_f32_e32 v75, v75
	v_or_b32_e32 v73, 32, v93
	v_cmp_lt_i32_e32 vcc, v73, v98
	v_max_f32_e32 v73, v68, v68
	v_add_f32_e32 v75, 1.0, v75
	v_cmp_gt_f32_e64 s[16:17], s81, v75
	v_min_f32_e32 v73, 0, v73
	s_and_b64 vcc, s[68:69], vcc
	v_cndmask_b32_e64 v97, 0, 32, s[16:17]
	v_ldexp_f32 v75, v75, v97
	v_log_f32_e32 v75, v75
	s_nop 0
	v_mul_f32_e32 v97, 0x3f317217, v75
	v_fma_f32 v97, v75, s48, -v97
	v_fmac_f32_e32 v97, 0x3377d1cf, v75
	v_fmac_f32_e32 v97, 0x3f317217, v75
	v_cmp_lt_f32_e64 s[18:19], |v75|, s49
	s_nop 1
	v_cndmask_b32_e64 v75, v75, v97, s[18:19]
	v_cndmask_b32_e64 v97, 0, v238, s[16:17]
	v_sub_f32_e32 v75, v75, v97
	v_mul_f32_e64 v97, |v69|, s93
	v_exp_f32_e32 v97, v97
	v_sub_f32_e32 v75, v73, v75
	v_cndmask_b32_e32 v73, v239, v75, vcc
	v_sub_f32_e32 v68, v75, v68
	v_add_f32_e32 v97, 1.0, v97
	v_cmp_gt_f32_e64 s[16:17], s81, v97
	v_or_b32_e32 v75, 33, v93
	v_cndmask_b32_e32 v68, 0, v68, vcc
	v_cndmask_b32_e64 v124, 0, 32, s[16:17]
	v_ldexp_f32 v97, v97, v124
	v_log_f32_e32 v97, v97
	v_cmp_lt_i32_e32 vcc, v75, v98
	v_max_f32_e32 v75, v69, v69
	v_min_f32_e32 v75, 0, v75
	v_mul_f32_e32 v124, 0x3f317217, v97
	v_fma_f32 v124, v97, s48, -v124
	v_fmac_f32_e32 v124, 0x3377d1cf, v97
	v_fmac_f32_e32 v124, 0x3f317217, v97
	v_cmp_lt_f32_e64 s[18:19], |v97|, s49
	s_and_b64 vcc, s[68:69], vcc
	s_nop 0
	v_cndmask_b32_e64 v97, v97, v124, s[18:19]
	v_cndmask_b32_e64 v124, 0, v238, s[16:17]
	v_sub_f32_e32 v97, v97, v124
	v_sub_f32_e32 v75, v75, v97
	v_cndmask_b32_e32 v97, v239, v75, vcc
	v_sub_f32_e32 v69, v75, v69
	v_mul_f32_e64 v75, |v70|, s93
	v_exp_f32_e32 v75, v75
	v_cndmask_b32_e32 v124, 0, v69, vcc
	v_or_b32_e32 v69, 34, v93
	v_cmp_lt_i32_e32 vcc, v69, v98
	v_add_f32_e32 v75, 1.0, v75
	v_cmp_gt_f32_e64 s[16:17], s81, v75
	v_max_f32_e32 v69, v70, v70
	v_min_f32_e32 v69, 0, v69
; DI float shdown(float v, int lane, int d) { return __builtin_bit_cast(float, __builtin_amdgcn_ds_bpermute(((lane + d) & 63) << 2, __builtin_bit_cast(int, v))); }
; DI void mix_sb(CP& p, int l, int it, LAS unsigned char* lds) {
;     ...
;     for (int kt = 0; kt < 4; ++kt) {
; #pragma unroll
;       for (int j = 0; j < 4; ++j) {
;         const float z = sc[kt][j];
;         const int spos = kb * 64 + kt * 16 + 4 * fq + j;
;         const bool causal = valid && (spos < tq);
;         const float lsv = fminf(z, 0.f) - __logf(1.f + __expf(-fabsf(z)));
;         ls[kt][j] = causal ? lsv : -1e30f;
;         lk[kt][j] = causal ? (lsv - z) : 0.f;
;       }
;       T[kt] = (lk[kt][0] + lk[kt][1]) + (lk[kt][2] + lk[kt][3]);
;       const float t1 = shdown(T[kt], lane, 16), t2 = shdown(T[kt], lane, 32), t3 = shdown(T[kt], lane, 48);
;       F[kt] = (fq < 3 ? t1 : 0.f) + (fq < 2 ? t2 : 0.f) + (fq < 1 ? t3 : 0.f);
;       float tt = T[kt] + shx<16>(T[kt], lane); tt += shx<32>(tt, lane); tot[kt] = tt;
	v_cndmask_b32_e64 v125, 0, 32, s[16:17]
	v_ldexp_f32 v75, v75, v125
	v_log_f32_e32 v75, v75
	s_and_b64 vcc, s[68:69], vcc
	v_add_f32_e32 v68, v68, v124
	v_mul_f32_e32 v125, 0x3f317217, v75
	v_fma_f32 v125, v75, s48, -v125
	v_fmac_f32_e32 v125, 0x3377d1cf, v75
	v_fmac_f32_e32 v125, 0x3f317217, v75
	v_cmp_lt_f32_e64 s[18:19], |v75|, s49
	s_nop 1
	v_cndmask_b32_e64 v75, v75, v125, s[18:19]
	v_cndmask_b32_e64 v125, 0, v238, s[16:17]
	v_sub_f32_e32 v75, v75, v125
	v_sub_f32_e32 v69, v69, v75
	v_mul_f32_e64 v75, |v71|, s93
	v_exp_f32_e32 v75, v75
	v_cndmask_b32_e32 v125, v239, v69, vcc
	v_sub_f32_e32 v69, v69, v70
	v_or_b32_e32 v70, 35, v93
	v_add_f32_e32 v75, 1.0, v75
	v_cmp_gt_f32_e64 s[16:17], s81, v75
	v_cndmask_b32_e32 v69, 0, v69, vcc
	v_cmp_lt_i32_e32 vcc, v70, v98
	v_cndmask_b32_e64 v126, 0, 32, s[16:17]
	v_ldexp_f32 v75, v75, v126
	v_log_f32_e32 v75, v75
	v_max_f32_e32 v70, v71, v71
	v_min_f32_e32 v70, 0, v70
	s_and_b64 vcc, s[68:69], vcc
	v_mul_f32_e32 v126, 0x3f317217, v75
	v_fma_f32 v126, v75, s48, -v126
	v_fmac_f32_e32 v126, 0x3377d1cf, v75
	v_fmac_f32_e32 v126, 0x3f317217, v75
	v_cmp_lt_f32_e64 s[18:19], |v75|, s49
	s_nop 1
	v_cndmask_b32_e64 v75, v75, v126, s[18:19]
	v_cndmask_b32_e64 v126, 0, v238, s[16:17]
	v_sub_f32_e32 v75, v75, v126
	v_sub_f32_e32 v70, v70, v75
	v_cndmask_b32_e32 v126, v239, v70, vcc
	v_sub_f32_e32 v70, v70, v71
	v_cndmask_b32_e32 v127, 0, v70, vcc
	v_add_f32_e32 v128, v69, v127
	v_add_f32_e32 v69, v68, v128
	ds_bpermute_b32 v71, v104, v69
	ds_bpermute_b32 v68, v103, v69
	ds_bpermute_b32 v75, v105, v69
	s_waitcnt lgkmcnt(2)
	v_cndmask_b32_e64 v146, 0, v71, s[10:11]
	ds_swizzle_b32 v71, v69 offset:swizzle(SWAP,16)
	s_waitcnt lgkmcnt(2)
	v_cndmask_b32_e64 v70, v68, 0, s[8:9]
	s_waitcnt lgkmcnt(1)
	v_cndmask_b32_e64 v68, 0, v75, s[12:13]
	s_waitcnt lgkmcnt(0)
	v_add_f32_e32 v69, v69, v71
	ds_bpermute_b32 v71, v104, v69
	s_waitcnt lgkmcnt(0)
	v_add_f32_e32 v75, v69, v71
	v_mul_f32_e64 v71, |v64|, s93
	v_exp_f32_e32 v71, v71
	v_or_b32_e32 v69, 48, v93
	v_cmp_lt_i32_e32 vcc, v69, v98
	v_max_f32_e32 v69, v64, v64
	v_add_f32_e32 v71, 1.0, v71
	v_cmp_gt_f32_e64 s[16:17], s81, v71
	v_min_f32_e32 v69, 0, v69
	s_and_b64 vcc, s[68:69], vcc
	v_cndmask_b32_e64 v129, 0, 32, s[16:17]
	v_ldexp_f32 v71, v71, v129
	v_log_f32_e32 v71, v71
	s_nop 0
	v_mul_f32_e32 v129, 0x3f317217, v71
	v_fma_f32 v129, v71, s48, -v129
	v_fmac_f32_e32 v129, 0x3377d1cf, v71
	v_fmac_f32_e32 v129, 0x3f317217, v71
	v_cmp_lt_f32_e64 s[18:19], |v71|, s49
	s_nop 1
	v_cndmask_b32_e64 v71, v71, v129, s[18:19]
	v_cndmask_b32_e64 v129, 0, v238, s[16:17]
	v_sub_f32_e32 v71, v71, v129
	v_sub_f32_e32 v69, v69, v71
	v_mul_f32_e64 v71, |v65|, s93
	v_exp_f32_e32 v71, v71
	v_cndmask_b32_e32 v129, v239, v69, vcc
	v_sub_f32_e32 v64, v69, v64
	v_or_b32_e32 v69, 49, v93
	v_add_f32_e32 v71, 1.0, v71
	v_cmp_gt_f32_e64 s[16:17], s81, v71
	v_cndmask_b32_e32 v64, 0, v64, vcc
	v_cmp_lt_i32_e32 vcc, v69, v98
	v_cndmask_b32_e64 v130, 0, 32, s[16:17]
	v_ldexp_f32 v71, v71, v130
	v_log_f32_e32 v71, v71
	v_max_f32_e32 v69, v65, v65
	v_min_f32_e32 v69, 0, v69
	s_and_b64 vcc, s[68:69], vcc
	v_mul_f32_e32 v130, 0x3f317217, v71
	v_fma_f32 v130, v71, s48, -v130
	v_fmac_f32_e32 v130, 0x3377d1cf, v71
	v_fmac_f32_e32 v130, 0x3f317217, v71
	v_cmp_lt_f32_e64 s[18:19], |v71|, s49
	s_nop 1
	v_cndmask_b32_e64 v71, v71, v130, s[18:19]
	v_cndmask_b32_e64 v130, 0, v238, s[16:17]
	v_sub_f32_e32 v71, v71, v130
	v_sub_f32_e32 v69, v69, v71
	v_mul_f32_e64 v71, |v66|, s93
	v_exp_f32_e32 v71, v71
	v_sub_f32_e32 v65, v69, v65
	v_cndmask_b32_e32 v130, v239, v69, vcc
	v_cndmask_b32_e32 v69, 0, v65, vcc
	v_add_f32_e32 v71, 1.0, v71
	v_cmp_gt_f32_e64 s[16:17], s81, v71
	v_or_b32_e32 v65, 50, v93
	v_cmp_lt_i32_e32 vcc, v65, v98
	v_cndmask_b32_e64 v131, 0, 32, s[16:17]
	v_ldexp_f32 v71, v71, v131
	v_log_f32_e32 v71, v71
	v_max_f32_e32 v65, v66, v66
	v_min_f32_e32 v65, 0, v65
	s_and_b64 vcc, s[68:69], vcc
	v_mul_f32_e32 v131, 0x3f317217, v71
	v_fma_f32 v131, v71, s48, -v131
	v_fmac_f32_e32 v131, 0x3377d1cf, v71
	v_fmac_f32_e32 v131, 0x3f317217, v71
	v_cmp_lt_f32_e64 s[18:19], |v71|, s49
	v_add_f32_e32 v64, v64, v69
	s_nop 0
	v_cndmask_b32_e64 v71, v71, v131, s[18:19]
	v_cndmask_b32_e64 v131, 0, v238, s[16:17]
	v_sub_f32_e32 v71, v71, v131
	v_sub_f32_e32 v65, v65, v71
	v_mul_f32_e64 v71, |v67|, s93
	v_exp_f32_e32 v71, v71
	v_cndmask_b32_e32 v131, v239, v65, vcc
	v_sub_f32_e32 v65, v65, v66
	v_or_b32_e32 v66, 51, v93
	v_add_f32_e32 v71, 1.0, v71
	v_cmp_gt_f32_e64 s[16:17], s81, v71
	v_cndmask_b32_e32 v65, 0, v65, vcc
	v_cmp_lt_i32_e32 vcc, v66, v98
	v_cndmask_b32_e64 v93, 0, 32, s[16:17]
	v_ldexp_f32 v71, v71, v93
	v_log_f32_e32 v71, v71
	v_max_f32_e32 v66, v67, v67
	v_min_f32_e32 v66, 0, v66
	s_and_b64 vcc, s[68:69], vcc
	v_mul_f32_e32 v93, 0x3f317217, v71
	v_fma_f32 v93, v71, s48, -v93
	v_fmac_f32_e32 v93, 0x3377d1cf, v71
	v_fmac_f32_e32 v93, 0x3f317217, v71
	v_cmp_lt_f32_e64 s[18:19], |v71|, s49
	s_nop 1
	v_cndmask_b32_e64 v71, v71, v93, s[18:19]
	v_cndmask_b32_e64 v93, 0, v238, s[16:17]
	v_sub_f32_e32 v71, v71, v93
	v_sub_f32_e32 v66, v66, v71
	v_cndmask_b32_e32 v132, v239, v66, vcc
	v_sub_f32_e32 v66, v66, v67
	v_cndmask_b32_e32 v66, 0, v66, vcc
	v_add_f32_e32 v67, v65, v66
	v_add_f32_e32 v64, v64, v67
	ds_bpermute_b32 v65, v103, v64
	ds_bpermute_b32 v71, v104, v64
	ds_bpermute_b32 v133, v105, v64
	s_andn2_b64 vcc, exec, s[72:73]
	s_waitcnt lgkmcnt(2)
	v_cndmask_b32_e64 v65, v65, 0, s[8:9]
	s_waitcnt lgkmcnt(1)
	v_cndmask_b32_e64 v71, 0, v71, s[10:11]
	v_add_f32_e32 v93, v65, v71
	ds_swizzle_b32 v71, v64 offset:swizzle(SWAP,16)
	s_waitcnt lgkmcnt(1)
	v_cndmask_b32_e64 v65, 0, v133, s[12:13]
	s_waitcnt lgkmcnt(0)
; DI unsigned pk2(float lo, float hi) { unsigned r; asm("v_cvt_pk_bf16_f32 %0, %1, %2" : "=v"(r) : "v"(lo), "v"(hi)); return r; }
; DI void mix_sb(CP& p, int l, int it, LAS unsigned char* lds) {
;     ...
;     float wgt[4][4];
;     {
;       float Ck = 0.f;
; #pragma unroll
;     ...
;         const float base = R + Ck + F[kt];
;         const float e3 = 0.f, e2 = lk[kt][3], e1 = e2 + lk[kt][2], e0 = e1 + lk[kt][1];
;         wgt[kt][0] = __expf(ls[kt][0] + base + e0); wgt[kt][1] = __expf(ls[kt][1] + base + e1);
;         wgt[kt][2] = __expf(ls[kt][2] + base + e2); wgt[kt][3] = __expf(ls[kt][3] + base + e3);
;         Ck += tot[kt];
;       }
;       R += Ck;
;     }
; #pragma unroll
;     for (int s = 0; s < 2; ++s) {
;       u32x4 wp; wp.x = pk2(wgt[2 * s][0], wgt[2 * s][1]); wp.y = pk2(wgt[2 * s][2], wgt[2 * s][3]); wp.z = pk2(wgt[2 * s + 1][0], wgt[2 * s + 1][1]); wp.w = pk2(wgt[2 * s + 1][2], wgt[2 * s + 1][3]);
;       const bf16x8 wf = __builtin_bit_cast(bf16x8, wp);
;       bf16x8 vf8[8]; gather_v8(vbuf, s, fr, fq, vf8);
; #pragma unroll
;       for (int c = 0; c < 8; ++c) o[c] = __builtin_amdgcn_mfma_f32_16x16x32_bf16(vf8[c], wf, o[c], 0, 0, 0);
;     }
;     if (kb > 0) SB_WRITE(cur ^ 1);
	v_add_f32_e32 v64, v64, v71
	ds_bpermute_b32 v71, v104, v64
	s_waitcnt lgkmcnt(0)
	v_add_f32_e32 v71, v64, v71
	v_mov_b32_e32 v64, v147
	v_pk_add_f32 v[64:65], v[92:93], v[64:65]
	s_nop 0
	v_add_f32_e32 v64, v64, v65
	v_add_f32_e32 v65, v69, v67
	v_add_f32_e32 v69, v129, v64
	v_add_f32_e32 v65, v65, v69
	v_mul_f32_e32 v65, 0x3fb8aa3b, v65
	v_exp_f32_e32 v93, v65
	v_add_f32_e32 v65, v130, v64
	v_add_f32_e32 v65, v67, v65
	v_mul_f32_e32 v65, 0x3fb8aa3b, v65
	v_exp_f32_e32 v135, v65
	v_add_f32_e32 v65, v131, v64
	v_add_f32_e32 v65, v66, v65
	v_add_f32_e32 v64, v132, v64
	v_mul_f32_e32 v65, 0x3fb8aa3b, v65
	v_mul_f32_e32 v64, 0x3fb8aa3b, v64
	v_exp_f32_e32 v140, v65
	v_exp_f32_e32 v141, v64
	v_pk_add_f32 v[64:65], v[70:71], v[146:147]
	v_mov_b32_e32 v69, v92
	v_pk_add_f32 v[66:67], v[64:65], v[68:69]
	s_nop 0
	v_add_f32_e32 v64, v66, v67
	v_add_f32_e32 v66, v124, v128
	v_add_f32_e32 v67, v73, v64
	v_add_f32_e32 v66, v66, v67
	v_mul_f32_e32 v66, 0x3fb8aa3b, v66
	v_exp_f32_e32 v142, v66
	v_add_f32_e32 v66, v97, v64
	v_add_f32_e32 v66, v128, v66
	v_mul_f32_e32 v66, 0x3fb8aa3b, v66
	v_exp_f32_e32 v143, v66
	v_add_f32_e32 v66, v125, v64
	v_add_f32_e32 v64, v126, v64
	v_add_f32_e32 v66, v127, v66
	v_mul_f32_e32 v64, 0x3fb8aa3b, v64
	v_mov_b32_e32 v97, v65
	v_mul_f32_e32 v66, 0x3fb8aa3b, v66
	v_exp_f32_e32 v148, v64
	v_pk_add_f32 v[64:65], v[74:75], v[96:97]
	v_mov_b32_e32 v73, v92
	v_exp_f32_e32 v146, v66
	v_pk_add_f32 v[66:67], v[64:65], v[72:73]
	s_nop 0
	v_add_f32_e32 v64, v66, v67
	v_add_f32_e32 v66, v119, v123
	v_add_f32_e32 v67, v77, v64
	v_add_f32_e32 v66, v66, v67
	v_mul_f32_e32 v66, 0x3fb8aa3b, v66
	v_exp_f32_e32 v68, v66
	v_add_f32_e32 v66, v95, v64
	v_add_f32_e32 v66, v123, v66
	v_mul_f32_e32 v66, 0x3fb8aa3b, v66
	v_exp_f32_e32 v69, v66
	v_add_f32_e32 v66, v120, v64
	v_add_f32_e32 v64, v121, v64
	v_add_f32_e32 v66, v122, v66
	v_mul_f32_e32 v64, 0x3fb8aa3b, v64
	v_mov_b32_e32 v95, v65
	v_mul_f32_e32 v66, 0x3fb8aa3b, v66
	v_exp_f32_e32 v71, v64
	v_pk_add_f32 v[64:65], v[78:79], v[94:95]
	v_mov_b32_e32 v77, v92
	v_exp_f32_e32 v70, v66
	v_pk_add_f32 v[66:67], v[64:65], v[76:77]
	v_cvt_pk_bf16_f32 v68, v68, v69
	v_cvt_pk_bf16_f32 v69, v70, v71
	s_nop 0
	v_add_f32_e32 v64, v66, v67
	v_add_f32_e32 v66, v114, v118
	v_add_f32_e32 v67, v112, v64
	v_add_f32_e32 v66, v66, v67
	v_add_f32_e32 v67, v113, v64
	v_add_f32_e32 v67, v118, v67
	v_add_f32_e32 v72, v115, v64
	v_add_f32_e32 v64, v116, v64
	v_mul_f32_e32 v66, 0x3fb8aa3b, v66
	v_mul_f32_e32 v67, 0x3fb8aa3b, v67
	v_add_f32_e32 v72, v117, v72
	v_mul_f32_e32 v64, 0x3fb8aa3b, v64
	v_exp_f32_e32 v66, v66
	v_exp_f32_e32 v67, v67
	v_mul_f32_e32 v72, 0x3fb8aa3b, v72
	v_exp_f32_e32 v64, v64
	v_exp_f32_e32 v72, v72
	v_cvt_pk_bf16_f32 v66, v66, v67
	v_cvt_pk_bf16_f32 v67, v72, v64
	v_add3_u32 v64, s24, v108, v106
	v_add_u32_e32 v72, 0x4400, v64
	ds_read_b64_tr_b16 v[128:129], v72
	ds_read_b64_tr_b16 v[124:125], v72 offset:32
	ds_read_b64_tr_b16 v[120:121], v72 offset:64
	ds_read_b64_tr_b16 v[116:117], v72 offset:96
	ds_read_b64_tr_b16 v[112:113], v72 offset:128
	ds_read_b64_tr_b16 v[94:95], v72 offset:160
	ds_read_b64_tr_b16 v[74:75], v72 offset:192
	ds_read_b64_tr_b16 v[70:71], v72 offset:224
	v_add_u32_e32 v118, 0x5480, v64
	ds_read_b64_tr_b16 v[72:73], v118
	ds_read_b64_tr_b16 v[76:77], v118 offset:32
	ds_read_b64_tr_b16 v[78:79], v118 offset:64
	ds_read_b64_tr_b16 v[96:97], v118 offset:96
	ds_read_b64_tr_b16 v[114:115], v118 offset:128
	ds_read_b64_tr_b16 v[132:133], v118 offset:160
	ds_read_b64_tr_b16 v[136:137], v118 offset:192
	ds_read_b64_tr_b16 v[138:139], v118 offset:224
	s_waitcnt lgkmcnt(0)
	s_nop 0
	v_mov_b32_e32 v130, v72
	v_mov_b32_e32 v131, v73
	v_mov_b32_e32 v126, v76
	v_mov_b32_e32 v127, v77
	v_mov_b32_e32 v122, v78
	v_mov_b32_e32 v123, v79
	v_mov_b32_e32 v118, v96
	v_mov_b32_e32 v119, v97
	v_mov_b32_e32 v96, v132
	v_mov_b32_e32 v97, v133
	v_mov_b32_e32 v76, v136
	v_mov_b32_e32 v77, v137
	v_mov_b32_e32 v72, v138
	v_mov_b32_e32 v73, v139
	v_mfma_f32_16x16x32_bf16 v[24:27], v[128:131], v[66:69], v[24:27]
	v_mfma_f32_16x16x32_bf16 v[28:31], v[124:127], v[66:69], v[28:31]
	v_mfma_f32_16x16x32_bf16 v[20:23], v[120:123], v[66:69], v[20:23]
	v_mfma_f32_16x16x32_bf16 v[16:19], v[116:119], v[66:69], v[16:19]
	v_mfma_f32_16x16x32_bf16 v[12:15], v[112:115], v[66:69], v[12:15]
	v_mfma_f32_16x16x32_bf16 v[8:11], v[94:97], v[66:69], v[8:11]
	v_mfma_f32_16x16x32_bf16 v[4:7], v[74:77], v[66:69], v[4:7]
	v_mfma_f32_16x16x32_bf16 v[0:3], v[70:73], v[66:69], v[0:3]
	v_add_u32_e32 v72, 0x6500, v64
	ds_read_b64_tr_b16 v[128:129], v72
	ds_read_b64_tr_b16 v[124:125], v72 offset:32
	ds_read_b64_tr_b16 v[120:121], v72 offset:64
	ds_read_b64_tr_b16 v[116:117], v72 offset:96
	ds_read_b64_tr_b16 v[112:113], v72 offset:128
	ds_read_b64_tr_b16 v[94:95], v72 offset:160
	ds_read_b64_tr_b16 v[74:75], v72 offset:192
	ds_read_b64_tr_b16 v[70:71], v72 offset:224
	v_add_u32_e32 v64, 0x7580, v64
	ds_read_b64_tr_b16 v[72:73], v64
	ds_read_b64_tr_b16 v[76:77], v64 offset:32
	ds_read_b64_tr_b16 v[78:79], v64 offset:64
	ds_read_b64_tr_b16 v[96:97], v64 offset:96
	ds_read_b64_tr_b16 v[114:115], v64 offset:128
	ds_read_b64_tr_b16 v[132:133], v64 offset:160
	ds_read_b64_tr_b16 v[136:137], v64 offset:192
	ds_read_b64_tr_b16 v[138:139], v64 offset:224
	s_waitcnt lgkmcnt(0)
	v_cvt_pk_bf16_f32 v66, v142, v143
	v_cvt_pk_bf16_f32 v67, v146, v148
	v_cvt_pk_bf16_f32 v68, v93, v135
	v_cvt_pk_bf16_f32 v69, v140, v141
	s_nop 0
	v_mov_b32_e32 v130, v72
	v_mov_b32_e32 v131, v73
	v_mov_b32_e32 v126, v76
	v_mov_b32_e32 v127, v77
	v_mov_b32_e32 v122, v78
	v_mov_b32_e32 v123, v79
	v_mov_b32_e32 v118, v96
	v_mov_b32_e32 v119, v97
	v_mov_b32_e32 v96, v132
	v_mov_b32_e32 v97, v133
	v_mov_b32_e32 v76, v136
	v_mov_b32_e32 v77, v137
	v_mov_b32_e32 v72, v138
	v_mov_b32_e32 v73, v139
	v_mfma_f32_16x16x32_bf16 v[24:27], v[128:131], v[66:69], v[24:27]
	v_mfma_f32_16x16x32_bf16 v[28:31], v[124:127], v[66:69], v[28:31]
	v_mfma_f32_16x16x32_bf16 v[20:23], v[120:123], v[66:69], v[20:23]
	v_mfma_f32_16x16x32_bf16 v[16:19], v[116:119], v[66:69], v[16:19]
	v_mfma_f32_16x16x32_bf16 v[12:15], v[112:115], v[66:69], v[12:15]
	v_mfma_f32_16x16x32_bf16 v[8:11], v[94:97], v[66:69], v[8:11]
	v_mfma_f32_16x16x32_bf16 v[4:7], v[74:77], v[66:69], v[4:7]
	v_mfma_f32_16x16x32_bf16 v[0:3], v[70:73], v[66:69], v[0:3]
	s_cbranch_vccnz .LBB0_228
	s_xor_b32 s0, s15, 1
	s_mul_i32 s0, s0, 0x8680
	v_lshlrev_b32_e32 v64, 1, v99
	v_add3_u32 v64, v100, s0, v64
	s_waitcnt vmcnt(3)
	ds_write_b128 v64, v[48:51]
	s_waitcnt vmcnt(2)
	ds_write_b128 v64, v[52:55] offset:16
	v_add_u32_e32 v64, v64, v101
	v_add_u32_e32 v66, 0x4400, v64
	v_add_u32_e32 v64, 0x4410, v64
	s_waitcnt vmcnt(1)
	ds_write2_b64 v66, v[56:57], v[58:59] offset1:1
	s_waitcnt vmcnt(0)
	ds_write2_b64 v64, v[60:61], v[62:63] offset1:1
